# deferred copies in the scan phase with one block in flight per wave instead of two (less memory-queue pressure on the scan)
# baseline (speedup 1.0000x reference)
; #define LAS __attribute__((address_space(3)))
; __device__ __forceinline__ void transpose_item(const float* W, int K, int N, bf16_t* WT, LAS float* scr, int item, int lane) {
;     const int nblk = (N + 31) / 32, kb = item / nblk, nb = item % nblk, k0 = 64 * kb, n0 = 32 * nb;
;     const int nn = n0 + (lane & 31); const bool ok = nn < N;
;     float v[32];
; #pragma unroll
;     for (int i = 0; i < 32; ++i) { const int kk = 2 * i + (lane >> 5); v[i] = ok ? W[(size_t)(k0 + kk) * N + nn] : 0.f; }
; #pragma unroll
;     for (int i = 0; i < 32; ++i) { const int kk = 2 * i + (lane >> 5); scr[kk * 33 + (lane & 31)] = v[i]; }
.Lp4t_la_p0_done:
	v_mad_u32_u24 v58, v0, s19, v2
	v_mad_u32_u24 v59, v0, s19, v3
	v_mad_u32_u24 v60, v0, s19, v4
	v_mad_u32_u24 v61, v0, s19, v5
	s_mov_b64 exec, s[34:35]
	s_mov_b32 m0, s6
	s_nop 0
	global_load_lds_dword v58, s[28:29]
	s_add_i32 m0, m0, 0x100
	s_add_u32 s28, s28, s32
	s_addc_u32 s29, s29, 0
	global_load_lds_dword v58, s[28:29]
	s_add_i32 m0, m0, 0x100
	s_add_u32 s28, s28, s32
	s_addc_u32 s29, s29, 0
	global_load_lds_dword v58, s[28:29]
	s_add_i32 m0, m0, 0x100
	s_add_u32 s28, s28, s32
	s_addc_u32 s29, s29, 0
	global_load_lds_dword v58, s[28:29]
	s_mov_b64 exec, s[34:35]
	s_add_i32 m0, m0, 0x100
	s_add_u32 s28, s28, s32
	s_addc_u32 s29, s29, 0
	global_load_lds_dword v59, s[28:29]
	s_add_i32 m0, m0, 0x100
	s_add_u32 s28, s28, s32
	s_addc_u32 s29, s29, 0
	global_load_lds_dword v59, s[28:29]
	s_add_i32 m0, m0, 0x100
	s_add_u32 s28, s28, s32
	s_addc_u32 s29, s29, 0
	global_load_lds_dword v59, s[28:29]
	s_add_i32 m0, m0, 0x100
	s_add_u32 s28, s28, s32
	s_addc_u32 s29, s29, 0
	global_load_lds_dword v59, s[28:29]
	s_mov_b64 exec, s[36:37]
	s_add_i32 m0, m0, 0x100
	s_add_u32 s28, s28, s32
	s_addc_u32 s29, s29, 0
	global_load_lds_dword v60, s[28:29]
	s_add_i32 m0, m0, 0x100
	s_add_u32 s28, s28, s32
	s_addc_u32 s29, s29, 0
	global_load_lds_dword v60, s[28:29]
	s_add_i32 m0, m0, 0x100
	s_add_u32 s28, s28, s32
	s_addc_u32 s29, s29, 0
	global_load_lds_dword v60, s[28:29]
	s_add_i32 m0, m0, 0x100
	s_add_u32 s28, s28, s32
	s_addc_u32 s29, s29, 0
	global_load_lds_dword v60, s[28:29]
	s_mov_b64 exec, s[36:37]
	s_add_i32 m0, m0, 0x100
	s_add_u32 s28, s28, s32
	s_addc_u32 s29, s29, 0
	global_load_lds_dword v61, s[28:29]
	s_add_i32 m0, m0, 0x100
	s_add_u32 s28, s28, s32
	s_addc_u32 s29, s29, 0
	global_load_lds_dword v61, s[28:29]
	s_add_i32 m0, m0, 0x100
	s_add_u32 s28, s28, s32
	s_addc_u32 s29, s29, 0
	global_load_lds_dword v61, s[28:29]
	s_add_i32 m0, m0, 0x100
	s_add_u32 s28, s28, s32
	s_addc_u32 s29, s29, 0
	global_load_lds_dword v61, s[28:29]
	s_mov_b64 exec, s[34:35]
	s_add_i32 m0, m0, 0x100
	s_add_u32 s28, s28, s32
	s_addc_u32 s29, s29, 0
	global_load_lds_dword v58, s[28:29]
	s_add_i32 m0, m0, 0x100
	s_add_u32 s28, s28, s32
	s_addc_u32 s29, s29, 0
	global_load_lds_dword v58, s[28:29]
	s_add_i32 m0, m0, 0x100
	s_add_u32 s28, s28, s32
	s_addc_u32 s29, s29, 0
	global_load_lds_dword v58, s[28:29]
	s_add_i32 m0, m0, 0x100
	s_add_u32 s28, s28, s32
	s_addc_u32 s29, s29, 0
	global_load_lds_dword v58, s[28:29]
	s_mov_b64 exec, s[34:35]
	s_add_i32 m0, m0, 0x100
	s_add_u32 s28, s28, s32
	s_addc_u32 s29, s29, 0
	global_load_lds_dword v59, s[28:29]
	s_add_i32 m0, m0, 0x100
	s_add_u32 s28, s28, s32
	s_addc_u32 s29, s29, 0
	global_load_lds_dword v59, s[28:29]
	s_add_i32 m0, m0, 0x100
	s_add_u32 s28, s28, s32
	s_addc_u32 s29, s29, 0
	global_load_lds_dword v59, s[28:29]
	s_add_i32 m0, m0, 0x100
	s_add_u32 s28, s28, s32
	s_addc_u32 s29, s29, 0
	global_load_lds_dword v59, s[28:29]
	s_mov_b64 exec, s[36:37]
	s_add_i32 m0, m0, 0x100
	s_add_u32 s28, s28, s32
	s_addc_u32 s29, s29, 0
	global_load_lds_dword v60, s[28:29]
	s_add_i32 m0, m0, 0x100
	s_add_u32 s28, s28, s32
	s_addc_u32 s29, s29, 0
	global_load_lds_dword v60, s[28:29]
	s_add_i32 m0, m0, 0x100
	s_add_u32 s28, s28, s32
	s_addc_u32 s29, s29, 0
	global_load_lds_dword v60, s[28:29]
	s_add_i32 m0, m0, 0x100
	s_add_u32 s28, s28, s32
	s_addc_u32 s29, s29, 0
	global_load_lds_dword v60, s[28:29]
	s_mov_b64 exec, s[36:37]
	s_add_i32 m0, m0, 0x100
	s_add_u32 s28, s28, s32
	s_addc_u32 s29, s29, 0
	global_load_lds_dword v61, s[28:29]
	s_add_i32 m0, m0, 0x100
	s_add_u32 s28, s28, s32
	s_addc_u32 s29, s29, 0
	global_load_lds_dword v61, s[28:29]
	s_add_i32 m0, m0, 0x100
	s_add_u32 s28, s28, s32
	s_addc_u32 s29, s29, 0
	global_load_lds_dword v61, s[28:29]
	s_add_i32 m0, m0, 0x100
	s_add_u32 s28, s28, s32
	s_addc_u32 s29, s29, 0
	global_load_lds_dword v61, s[28:29]
	s_mov_b64 exec, -1
	s_add_i32 s5, s4, s18
.Lp4t_loop:
	s_mov_b32 s7, s4
	s_mov_b64 s[48:49], 0
	s_cmp_ge_u32 s7, 0x2020
	s_cselect_b32 s70, s99, s98
	s_add_u32 s7, s7, s70
	s_cmp_ge_u32 s7, 0x8080
	s_cbranch_scc1 .Lp4t_sa_out
	s_mul_hi_u32 s38, s7, 0x7f808
	s_mul_i32 s70, s38, 0x2020
	s_sub_u32 s7, s7, s70
	s_mul_hi_u32 s55, s7, 0xff0100
	s_mul_i32 s70, s55, 0x101
	s_sub_u32 s7, s7, s70
	s_mul_i32 s70, s38, 0x2020000
	s_cmp_eq_u32 s7, 0x100
	s_cselect_b32 s48, -1, 0
	s_mov_b32 s49, s48
	s_branch .Lp4t_sa_done

; #define LAS __attribute__((address_space(3)))
; __device__ __forceinline__ unsigned pk2(float lo, float hi) { return pg8::cvt_pk_bf16(lo, hi); }
; #define LDS_WAIT() asm volatile("s_waitcnt lgkmcnt(0)" ::: "memory")
; __device__ __forceinline__ void transpose_item(const float* W, int K, int N, bf16_t* WT, LAS float* scr, int item, int lane) {
;     ...
;     const int c = lane & 7;
; #pragma unroll
;     for (int j = 0; j < 4; ++j) { const int n = (lane >> 3) + 8 * j; const LAS float* s = scr + (8 * c) * 33 + n;
;         u32x4 o; o.x = pk2(s[0 * 33], s[1 * 33]); o.y = pk2(s[2 * 33], s[3 * 33]); o.z = pk2(s[4 * 33], s[5 * 33]); o.w = pk2(s[6 * 33], s[7 * 33]);
;         *(u32x4*)(WT + (size_t)(n0 + n) * K + k0 + 8 * c) = o; }
;     LDS_WAIT(); asm volatile("" ::: "memory");
; }
.Lp4t_sa_done:
	s_lshl_b32 s71, s7, 17
	s_add_u32 s70, s70, s71
	s_lshl_b32 s71, s55, 7
	s_add_u32 s70, s70, s71
	s_add_u32 s30, s26, s70
	s_addc_u32 s31, s27, 0
	s_waitcnt vmcnt(0)
	ds_read2_b32 v[18:19], v62 offset0:0 offset1:32
	ds_read2_b32 v[20:21], v62 offset0:64 offset1:96
	ds_read2_b32 v[22:23], v62 offset0:128 offset1:160
	ds_read2_b32 v[24:25], v62 offset0:192 offset1:224
	ds_read2_b32 v[26:27], v63 offset0:0 offset1:32
	ds_read2_b32 v[28:29], v63 offset0:64 offset1:96
	ds_read2_b32 v[30:31], v63 offset0:128 offset1:160
	ds_read2_b32 v[32:33], v63 offset0:192 offset1:224
	ds_read2_b32 v[34:35], v64 offset0:0 offset1:32
	ds_read2_b32 v[36:37], v64 offset0:64 offset1:96
	ds_read2_b32 v[38:39], v64 offset0:128 offset1:160
	ds_read2_b32 v[40:41], v64 offset0:192 offset1:224
	ds_read2_b32 v[42:43], v65 offset0:0 offset1:32
	ds_read2_b32 v[44:45], v65 offset0:64 offset1:96
	ds_read2_b32 v[46:47], v65 offset0:128 offset1:160
	ds_read2_b32 v[48:49], v65 offset0:192 offset1:224
	s_waitcnt lgkmcnt(12)
	v_cvt_pk_bf16_f32 v50, v18, v19
	v_cvt_pk_bf16_f32 v51, v20, v21
	v_cvt_pk_bf16_f32 v52, v22, v23
	v_cvt_pk_bf16_f32 v53, v24, v25
	global_store_dwordx4 v13, v[50:53], s[30:31]
	s_waitcnt lgkmcnt(8)
	v_cvt_pk_bf16_f32 v54, v26, v27
	v_cvt_pk_bf16_f32 v55, v28, v29
	v_cvt_pk_bf16_f32 v56, v30, v31
	v_cvt_pk_bf16_f32 v57, v32, v33
	global_store_dwordx4 v14, v[54:57], s[30:31]
	s_waitcnt lgkmcnt(4)
	v_cvt_pk_bf16_f32 v50, v34, v35
	v_cvt_pk_bf16_f32 v51, v36, v37
	v_cvt_pk_bf16_f32 v52, v38, v39
	v_cvt_pk_bf16_f32 v53, v40, v41
	v_cndmask_b32_e64 v50, v50, 0, s[48:49]
	v_cndmask_b32_e64 v51, v51, 0, s[48:49]
	v_cndmask_b32_e64 v52, v52, 0, s[48:49]
	v_cndmask_b32_e64 v53, v53, 0, s[48:49]
	global_store_dwordx4 v15, v[50:53], s[30:31]
	s_waitcnt lgkmcnt(0)
	v_cvt_pk_bf16_f32 v54, v42, v43
	v_cvt_pk_bf16_f32 v55, v44, v45
	v_cvt_pk_bf16_f32 v56, v46, v47
	v_cvt_pk_bf16_f32 v57, v48, v49
	v_cndmask_b32_e64 v54, v54, 0, s[48:49]
	v_cndmask_b32_e64 v55, v55, 0, s[48:49]
	v_cndmask_b32_e64 v56, v56, 0, s[48:49]
	v_cndmask_b32_e64 v57, v57, 0, s[48:49]
	global_store_dwordx4 v16, v[54:57], s[30:31]
	s_cmp_lt_i32 s5, s16
	s_cbranch_scc0 .Lp4t_nopf
	s_mov_b32 s7, s5
	s_cmp_ge_u32 s7, 0x2020
	s_cselect_b32 s70, s99, s98
	s_add_u32 s7, s7, s70
	s_cmp_ge_u32 s7, 0x8080
	s_cbranch_scc1 .Lp4t_la_lp_out
	s_mul_hi_u32 s38, s7, 0x7f808
	s_mul_i32 s70, s38, 0x2020
	s_sub_u32 s7, s7, s70
	s_mul_hi_u32 s55, s7, 0xff0100
	s_mul_i32 s70, s55, 0x101
	s_sub_u32 s7, s7, s70
	s_mul_i32 s70, s38, 0x4020000
	s_mul_i32 s71, s55, 0x201000
	s_add_u32 s70, s70, s71
	s_lshl_b32 s71, s7, 7
	s_add_u32 s70, s70, s71
	s_add_u32 s28, s22, s70
	s_addc_u32 s29, s23, 0
	s_mov_b32 s19, 0x8040
	s_mov_b32 s32, 0x10080
	s_mov_b64 s[34:35], -1
	s_mov_b64 s[36:37], -1
	s_cmp_eq_u32 s7, 0x100
	s_cbranch_scc0 .Lp4t_la_lp_done
	s_mov_b32 s34, 0xffff
	s_mov_b32 s35, 0xffff
	s_mov_b32 s36, 0xffff0000
	s_mov_b32 s37, 0xffff0000
	s_branch .Lp4t_la_lp_done

; __global__ void __launch_bounds__(512, 2) mega(Args a) {
;     ...
;         for (int it = it0; it < itN; it += its) {
;             int r = it;
;             if (r < 4 * I_IN) { const int l = r / I_IN; r -= l * I_IN; transpose_item(((const float*)ap->in[10]) + (size_t)l * DM * DIN, DM, DIN, WSP(bf16_t, WS_WIN) + (size_t)l * DINP * DM, scr, r, lane); }
;             else { r -= 4 * I_IN; const int l = r / I_OUT; r -= l * I_OUT; transpose_item(((const float*)ap->in[16]) + (size_t)l * DM * DM, DM, DM, WSP(bf16_t, WS_WOUT) + (size_t)l * DM * DM, scr, r, lane); }
;         }
.Lp4t_nopf:
	s_add_i32 s5, s5, s18
	s_add_i32 s4, s4, s18
	s_cmp_lt_i32 s4, s16
	s_cbranch_scc1 .Lp4t_loop
	s_waitcnt vmcnt(0)
